# M4 (output RMSNorms) fused into end of M3: units remapped so a CU owns both B/C groups of a chunk; one grid barrier and the M4 phase removed
# speedup vs baseline: 1.0212x; 1.0036x over previous
; #define PHASE_IDS() const int tid = opaque_tid(), lane = tid & 63, r16 = lane & 15, q4 = lane >> 4; (void)r16; (void)q4; (void)tid
; __global__ void __launch_bounds__(512, 2) fwd_megakernel(Args args) {
;     ...
;             for (int rp_ = 0; rp_ < ((REPMASK & 128) ? 2 : 1); ++rp_)
;             for (int unit = bid; unit < BATCH * NCH * 2; unit += G) {
;                 PHASE_IDS();
;                 const int g2 = unit & 1, c = (unit >> 1) & 31, b = unit >> 6;
;                 const size_t grow0 = (size_t)b * SEQ + c * 128;
.LBB0_924:
	s_or_b64 exec, exec, s[4:5]
	v_readlane_b32 s28, v253, 17
	s_and_b64 vcc, exec, s[26:27]
	v_readlane_b32 s29, v253, 18
	s_lshl_b32 s83, s54, 1
	s_waitcnt lgkmcnt(0)
	s_barrier
	s_cbranch_vccz .LBB0_929

; #define PHASE_IDS() const int tid = opaque_tid(), lane = tid & 63, r16 = lane & 15, q4 = lane >> 4; (void)r16; (void)q4; (void)tid
; __global__ void __launch_bounds__(512, 2) fwd_megakernel(Args args) {
;     ...
;             for (int unit = bid; unit < BATCH * NCH * 2; unit += G) {
;                 PHASE_IDS();
;                 const int g2 = unit & 1, c = (unit >> 1) & 31, b = unit >> 6;
;                 const size_t grow0 = (size_t)b * SEQ + c * 128;
.LBB0_928:
	v_readlane_b32 s2, v253, 21
	v_readlane_b32 s3, v253, 22
	s_add_i32 s83, s83, 1
	s_xor_b64 s[28:29], s[96:97], s[2:3]
	v_readlane_b32 s56, v253, 32
	s_bitcmp0_b32 s83, 0
	s_mov_b32 s86, s33
	s_mov_b64 s[94:95], s[84:85]
	s_mov_b64 s[84:85], s[92:93]
	s_mov_b64 s[92:93], s[90:91]
	v_readlane_b32 s87, v253, 36
	v_readlane_b32 s90, v253, 34
	s_mov_b32 s91, s78
	v_readlane_b32 s96, v253, 35
	v_readlane_b32 s97, v253, 31
	v_readlane_b32 s57, v253, 33
	s_movk_i32 s33, 0x230
	s_mov_b32 s59, s79
	s_waitcnt lgkmcnt(0)
	s_barrier
	s_cbranch_scc1 .Lm4f

; DI u32x4 pack8(const float (&v)[8]) { u32x4 r; r.x = pk2(v[0], v[1]); r.y = pk2(v[2], v[3]); r.z = pk2(v[4], v[5]); r.w = pk2(v[6], v[7]); return r; }
; __global__ void __launch_bounds__(512, 2) fwd_megakernel(Args args) {
;     ...
;                 for (int r = 0; r < 4; ++r) { const int m = min(m0 + r * NGW, MTOK - 1);
;                     sv[r][0] = *(const f32x4*)(mss_g + (size_t)m * 4); sv[r][1] = *(const f32x4*)(mss_g + ((size_t)MTOK + m) * 4); sv[r][2] = (f32x4){mss_a[m], mss_a[(size_t)MTOK + m], mss_a[(size_t)2 * MTOK + m], mss_a[(size_t)3 * MTOK + m]};
;                     yv[r][0] = *(const u32x4*)(Yg + (size_t)m * DM + colA); yv[r][1] = *(const u32x4*)(Yg + (size_t)m * DM + 512 + (lane & 31) * 8); }
;                 float nwA[8], nwB[8];
;                 { const float* p = args.in[12] + layer * 512 + colA;
; #pragma unroll
;                   for (int i = 0; i < 8; ++i) nwA[i] = p[i];
;                   const float* q = args.in[15] + layer * 256 + (lane & 31) * 8;
; #pragma unroll
;                   for (int i = 0; i < 8; ++i) nwB[i] = q[i]; }
; #pragma unroll
;                 for (int r = 0; r < 4; ++r) { const int m = m0 + r * NGW; if (m < MTOK) {
;                     const f32x4 s0 = sv[r][0], s1 = sv[r][1], s2 = sv[r][2];
;                     const float r_ssd = rsqrtf((((s0.x + s0.y) + (s0.z + s0.w)) + ((s1.x + s1.y) + (s1.z + s1.w))) * (1.f / 512.f) + EPS);
;                     const float r_att = rsqrtf(((s2.x + s2.y) + (s2.z + s2.w)) * (1.f / 256.f) + EPS);
;                     float v[8]; unpack8(yv[r][0], v);
; #pragma unroll
;                     for (int i = 0; i < 8; ++i) v[i] = v[i] * r_ssd * nwA[i];
;                     *(u32x4*)(ycat + (size_t)m * DM + colA) = pack8(v);
.Lm4f:
	s_waitcnt vmcnt(0) lgkmcnt(0)
	s_barrier
	v_readlane_b32 s2, v252, 0
	v_readlane_b32 s3, v251, 0
	s_lshl_b32 s3, s3, 7
	s_lshl_b32 s29, s2, 4
	s_add_i32 s3, s3, s29
	s_lshl_b32 s29, s3, 11
	s_add_u32 s4, s80, 0xa000000
	s_addc_u32 s5, s81, 0
	s_add_u32 s4, s4, s29
	s_addc_u32 s5, s5, 0
	s_add_u32 s6, s80, 0xe000000
	s_addc_u32 s7, s81, 0
	s_add_u32 s6, s6, s29
	s_addc_u32 s7, s7, 0
	s_lshl_b32 s29, s3, 4
	s_add_u32 s8, s80, 0x300000
	s_addc_u32 s9, s81, 0
	s_add_u32 s8, s8, s29
	s_addc_u32 s9, s9, 0
	s_lshl_b32 s29, s3, 2
	s_add_u32 s12, s80, 0x400000
	s_addc_u32 s13, s81, 0
	s_add_u32 s12, s12, s29
	s_addc_u32 s13, s13, 0
	v_readlane_b32 s29, v253, 58
	v_readlane_b32 s30, v251, 33
	v_readlane_b32 s31, v251, 34
	s_lshl_b32 s10, s29, 8
	s_add_u32 s30, s30, s10
	s_addc_u32 s31, s31, 0
	v_readlane_b32 s34, v251, 39
	v_readlane_b32 s35, v251, 40
	s_lshl_b32 s10, s29, 7
	s_add_u32 s34, s34, s10
	s_addc_u32 s35, s35, 0
	v_and_b32_e32 v116, 63, v195
	v_and_b32_e32 v161, 15, v116
	v_bfe_u32 v162, v116, 4, 2
	v_and_b32_e32 v163, 1, v162
	v_lshlrev_b32_e32 v163, 19, v163
	v_lshl_add_u32 v163, v161, 4, v163
	global_load_dwordx4 v[134:137], v163, s[8:9]
	v_lshlrev_b32_e32 v163, 17, v162
	v_lshl_add_u32 v163, v161, 2, v163
	global_load_dword v138, v163, s[12:13]
	v_lshlrev_b32_e32 v163, 5, v116
	global_load_dwordx4 v[118:121], v163, s[30:31]
	global_load_dwordx4 v[122:125], v163, s[30:31] offset:16
	v_and_b32_e32 v164, 31, v116
	v_lshlrev_b32_e32 v164, 5, v164
	global_load_dwordx4 v[126:129], v164, s[34:35]
	global_load_dwordx4 v[130:133], v164, s[34:35] offset:16
	v_xor_b32_e32 v165, 16, v116
	v_lshlrev_b32_e32 v165, 2, v165
	v_xor_b32_e32 v166, 32, v116
	v_lshlrev_b32_e32 v166, 2, v166
	v_lshlrev_b32_e32 v117, 4, v116
	s_waitcnt vmcnt(4)
	v_add_f32_e32 v134, v134, v135
	v_add_f32_e32 v136, v136, v137
	v_add_f32_e32 v134, v134, v136
	ds_bpermute_b32 v135, v165, v134
	ds_bpermute_b32 v139, v165, v138
	s_waitcnt lgkmcnt(0)
	v_add_f32_e32 v134, v134, v135
	v_add_f32_e32 v138, v138, v139
	ds_bpermute_b32 v139, v166, v138
	v_mov_b32_e32 v167, 0x358637bd
	v_fmamk_f32 v154, v134, 0x3b000000, v167
	v_rsq_f32_e32 v154, v154
	s_waitcnt lgkmcnt(0)
	v_add_f32_e32 v138, v138, v139
	v_fmamk_f32 v160, v138, 0x3b800000, v167
	v_rsq_f32_e32 v160, v160
	s_nop 0
	v_readlane_b32 s60, v154, 0
	v_readlane_b32 s61, v154, 1
	v_readlane_b32 s62, v154, 2
	v_readlane_b32 s63, v154, 3
	v_readlane_b32 s64, v154, 4
	v_readlane_b32 s65, v154, 5
	v_readlane_b32 s66, v154, 6
	v_readlane_b32 s67, v154, 7
	v_readlane_b32 s68, v154, 8
	v_readlane_b32 s69, v154, 9
	v_readlane_b32 s70, v154, 10
	v_readlane_b32 s71, v154, 11
	v_readlane_b32 s72, v154, 12
	v_readlane_b32 s73, v154, 13
	v_readlane_b32 s74, v154, 14
	v_readlane_b32 s75, v154, 15
	s_waitcnt vmcnt(0)
	v_add_u32_e32 v169, 0, v117
	global_load_dwordx4 v[170:173], v169, s[4:5]
	v_add_u32_e32 v169, 2048, v117
	global_load_dwordx4 v[174:177], v169, s[4:5]
	v_add_u32_e32 v169, 4096, v117
	global_load_dwordx4 v[178:181], v169, s[4:5]
	v_add_u32_e32 v169, 6144, v117
	global_load_dwordx4 v[182:185], v169, s[4:5]
	s_waitcnt vmcnt(3)
	v_add_u32_e32 v169, 0, v117
	v_lshlrev_b32_e32 v142, 16, v170
	v_and_b32_e32 v143, 0xffff0000, v170
	v_lshlrev_b32_e32 v144, 16, v171
	v_and_b32_e32 v145, 0xffff0000, v171
	v_lshlrev_b32_e32 v146, 16, v172
	v_and_b32_e32 v147, 0xffff0000, v172
	v_lshlrev_b32_e32 v148, 16, v173
	v_and_b32_e32 v149, 0xffff0000, v173
	v_mul_f32_e32 v142, s60, v142
	v_mul_f32_e32 v143, s60, v143
	v_mul_f32_e32 v144, s60, v144
	v_mul_f32_e32 v145, s60, v145
	v_mul_f32_e32 v146, s60, v146
	v_mul_f32_e32 v147, s60, v147
	v_mul_f32_e32 v148, s60, v148
	v_mul_f32_e32 v149, s60, v149
	v_mul_f32_e32 v142, v142, v118
	v_mul_f32_e32 v143, v143, v119
	v_mul_f32_e32 v144, v144, v120
	v_mul_f32_e32 v145, v145, v121
	v_mul_f32_e32 v146, v146, v122
	v_mul_f32_e32 v147, v147, v123
	v_mul_f32_e32 v148, v148, v124
	v_mul_f32_e32 v149, v149, v125
	v_cvt_pk_bf16_f32 v150, v142, v143
	v_cvt_pk_bf16_f32 v151, v144, v145
	v_cvt_pk_bf16_f32 v152, v146, v147
	v_cvt_pk_bf16_f32 v153, v148, v149
	global_store_dwordx4 v169, v[150:153], s[6:7] offset:0
	s_nop 1
	s_waitcnt vmcnt(2)
	v_add_u32_e32 v169, 2048, v117
	v_lshlrev_b32_e32 v142, 16, v174
	v_and_b32_e32 v143, 0xffff0000, v174
	v_lshlrev_b32_e32 v144, 16, v175
	v_and_b32_e32 v145, 0xffff0000, v175
	v_lshlrev_b32_e32 v146, 16, v176
	v_and_b32_e32 v147, 0xffff0000, v176
	v_lshlrev_b32_e32 v148, 16, v177
	v_and_b32_e32 v149, 0xffff0000, v177
	v_mul_f32_e32 v142, s61, v142
	v_mul_f32_e32 v143, s61, v143
	v_mul_f32_e32 v144, s61, v144
	v_mul_f32_e32 v145, s61, v145
	v_mul_f32_e32 v146, s61, v146
	v_mul_f32_e32 v147, s61, v147
	v_mul_f32_e32 v148, s61, v148
	v_mul_f32_e32 v149, s61, v149
	v_mul_f32_e32 v142, v142, v118
	v_mul_f32_e32 v143, v143, v119
	v_mul_f32_e32 v144, v144, v120
	v_mul_f32_e32 v145, v145, v121
	v_mul_f32_e32 v146, v146, v122
	v_mul_f32_e32 v147, v147, v123
	v_mul_f32_e32 v148, v148, v124
	v_mul_f32_e32 v149, v149, v125
	v_cvt_pk_bf16_f32 v150, v142, v143
	v_cvt_pk_bf16_f32 v151, v144, v145
	v_cvt_pk_bf16_f32 v152, v146, v147
	v_cvt_pk_bf16_f32 v153, v148, v149
	global_store_dwordx4 v169, v[150:153], s[6:7] offset:0
	s_nop 1
	s_waitcnt vmcnt(1)
; DI u32x4 pack8(const float (&v)[8]) { u32x4 r; r.x = pk2(v[0], v[1]); r.y = pk2(v[2], v[3]); r.z = pk2(v[4], v[5]); r.w = pk2(v[6], v[7]); return r; }
; __global__ void __launch_bounds__(512, 2) fwd_megakernel(Args args) {
;     ...
;                 for (int r = 0; r < 4; ++r) { const int m = m0 + r * NGW; if (m < MTOK) {
;                     const f32x4 s0 = sv[r][0], s1 = sv[r][1], s2 = sv[r][2];
;                     const float r_ssd = rsqrtf((((s0.x + s0.y) + (s0.z + s0.w)) + ((s1.x + s1.y) + (s1.z + s1.w))) * (1.f / 512.f) + EPS);
;                     const float r_att = rsqrtf(((s2.x + s2.y) + (s2.z + s2.w)) * (1.f / 256.f) + EPS);
;                     float v[8]; unpack8(yv[r][0], v);
; #pragma unroll
;                     for (int i = 0; i < 8; ++i) v[i] = v[i] * r_ssd * nwA[i];
;                     *(u32x4*)(ycat + (size_t)m * DM + colA) = pack8(v);
	v_add_u32_e32 v169, 4096, v117
	v_lshlrev_b32_e32 v142, 16, v178
	v_and_b32_e32 v143, 0xffff0000, v178
	v_lshlrev_b32_e32 v144, 16, v179
	v_and_b32_e32 v145, 0xffff0000, v179
	v_lshlrev_b32_e32 v146, 16, v180
	v_and_b32_e32 v147, 0xffff0000, v180
	v_lshlrev_b32_e32 v148, 16, v181
	v_and_b32_e32 v149, 0xffff0000, v181
	v_mul_f32_e32 v142, s62, v142
	v_mul_f32_e32 v143, s62, v143
	v_mul_f32_e32 v144, s62, v144
	v_mul_f32_e32 v145, s62, v145
	v_mul_f32_e32 v146, s62, v146
	v_mul_f32_e32 v147, s62, v147
	v_mul_f32_e32 v148, s62, v148
	v_mul_f32_e32 v149, s62, v149
	v_mul_f32_e32 v142, v142, v118
	v_mul_f32_e32 v143, v143, v119
	v_mul_f32_e32 v144, v144, v120
	v_mul_f32_e32 v145, v145, v121
	v_mul_f32_e32 v146, v146, v122
	v_mul_f32_e32 v147, v147, v123
	v_mul_f32_e32 v148, v148, v124
	v_mul_f32_e32 v149, v149, v125
	v_cvt_pk_bf16_f32 v150, v142, v143
	v_cvt_pk_bf16_f32 v151, v144, v145
	v_cvt_pk_bf16_f32 v152, v146, v147
	v_cvt_pk_bf16_f32 v153, v148, v149
	global_store_dwordx4 v169, v[150:153], s[6:7] offset:0
	s_nop 1
	s_waitcnt vmcnt(0)
	v_add_u32_e32 v169, 6144, v117
	v_lshlrev_b32_e32 v142, 16, v182
	v_and_b32_e32 v143, 0xffff0000, v182
	v_lshlrev_b32_e32 v144, 16, v183
	v_and_b32_e32 v145, 0xffff0000, v183
	v_lshlrev_b32_e32 v146, 16, v184
	v_and_b32_e32 v147, 0xffff0000, v184
	v_lshlrev_b32_e32 v148, 16, v185
	v_and_b32_e32 v149, 0xffff0000, v185
	v_mul_f32_e32 v142, s63, v142
	v_mul_f32_e32 v143, s63, v143
	v_mul_f32_e32 v144, s63, v144
	v_mul_f32_e32 v145, s63, v145
	v_mul_f32_e32 v146, s63, v146
	v_mul_f32_e32 v147, s63, v147
	v_mul_f32_e32 v148, s63, v148
	v_mul_f32_e32 v149, s63, v149
	v_mul_f32_e32 v142, v142, v118
	v_mul_f32_e32 v143, v143, v119
	v_mul_f32_e32 v144, v144, v120
	v_mul_f32_e32 v145, v145, v121
	v_mul_f32_e32 v146, v146, v122
	v_mul_f32_e32 v147, v147, v123
	v_mul_f32_e32 v148, v148, v124
	v_mul_f32_e32 v149, v149, v125
	v_cvt_pk_bf16_f32 v150, v142, v143
	v_cvt_pk_bf16_f32 v151, v144, v145
	v_cvt_pk_bf16_f32 v152, v146, v147
	v_cvt_pk_bf16_f32 v153, v148, v149
	global_store_dwordx4 v169, v[150:153], s[6:7] offset:0
	s_nop 1
	v_add_u32_e32 v169, 8192, v117
	global_load_dwordx4 v[170:173], v169, s[4:5]
	v_add_u32_e32 v169, 10240, v117
	global_load_dwordx4 v[174:177], v169, s[4:5]
	v_add_u32_e32 v169, 12288, v117
	global_load_dwordx4 v[178:181], v169, s[4:5]
	v_add_u32_e32 v169, 14336, v117
	global_load_dwordx4 v[182:185], v169, s[4:5]
	s_waitcnt vmcnt(3)
	v_add_u32_e32 v169, 8192, v117
	v_lshlrev_b32_e32 v142, 16, v170
	v_and_b32_e32 v143, 0xffff0000, v170
	v_lshlrev_b32_e32 v144, 16, v171
	v_and_b32_e32 v145, 0xffff0000, v171
	v_lshlrev_b32_e32 v146, 16, v172
	v_and_b32_e32 v147, 0xffff0000, v172
	v_lshlrev_b32_e32 v148, 16, v173
	v_and_b32_e32 v149, 0xffff0000, v173
	v_mul_f32_e32 v142, s64, v142
	v_mul_f32_e32 v143, s64, v143
	v_mul_f32_e32 v144, s64, v144
	v_mul_f32_e32 v145, s64, v145
	v_mul_f32_e32 v146, s64, v146
	v_mul_f32_e32 v147, s64, v147
	v_mul_f32_e32 v148, s64, v148
	v_mul_f32_e32 v149, s64, v149
	v_mul_f32_e32 v142, v142, v118
	v_mul_f32_e32 v143, v143, v119
	v_mul_f32_e32 v144, v144, v120
	v_mul_f32_e32 v145, v145, v121
	v_mul_f32_e32 v146, v146, v122
	v_mul_f32_e32 v147, v147, v123
	v_mul_f32_e32 v148, v148, v124
	v_mul_f32_e32 v149, v149, v125
	v_cvt_pk_bf16_f32 v150, v142, v143
	v_cvt_pk_bf16_f32 v151, v144, v145
	v_cvt_pk_bf16_f32 v152, v146, v147
	v_cvt_pk_bf16_f32 v153, v148, v149
	global_store_dwordx4 v169, v[150:153], s[6:7] offset:0
	s_nop 1
	s_waitcnt vmcnt(2)
	v_add_u32_e32 v169, 10240, v117
	v_lshlrev_b32_e32 v142, 16, v174
	v_and_b32_e32 v143, 0xffff0000, v174
	v_lshlrev_b32_e32 v144, 16, v175
	v_and_b32_e32 v145, 0xffff0000, v175
	v_lshlrev_b32_e32 v146, 16, v176
	v_and_b32_e32 v147, 0xffff0000, v176
	v_lshlrev_b32_e32 v148, 16, v177
	v_and_b32_e32 v149, 0xffff0000, v177
	v_mul_f32_e32 v142, s65, v142
	v_mul_f32_e32 v143, s65, v143
	v_mul_f32_e32 v144, s65, v144
	v_mul_f32_e32 v145, s65, v145
	v_mul_f32_e32 v146, s65, v146
	v_mul_f32_e32 v147, s65, v147
	v_mul_f32_e32 v148, s65, v148
	v_mul_f32_e32 v149, s65, v149
	v_mul_f32_e32 v142, v142, v118
	v_mul_f32_e32 v143, v143, v119
	v_mul_f32_e32 v144, v144, v120
	v_mul_f32_e32 v145, v145, v121
	v_mul_f32_e32 v146, v146, v122
	v_mul_f32_e32 v147, v147, v123
	v_mul_f32_e32 v148, v148, v124
	v_mul_f32_e32 v149, v149, v125
	v_cvt_pk_bf16_f32 v150, v142, v143
	v_cvt_pk_bf16_f32 v151, v144, v145
	v_cvt_pk_bf16_f32 v152, v146, v147
	v_cvt_pk_bf16_f32 v153, v148, v149
	global_store_dwordx4 v169, v[150:153], s[6:7] offset:0
	s_nop 1
	s_waitcnt vmcnt(1)
	v_add_u32_e32 v169, 12288, v117
	v_lshlrev_b32_e32 v142, 16, v178
	v_and_b32_e32 v143, 0xffff0000, v178
	v_lshlrev_b32_e32 v144, 16, v179
	v_and_b32_e32 v145, 0xffff0000, v179
	v_lshlrev_b32_e32 v146, 16, v180
	v_and_b32_e32 v147, 0xffff0000, v180
	v_lshlrev_b32_e32 v148, 16, v181
	v_and_b32_e32 v149, 0xffff0000, v181
	v_mul_f32_e32 v142, s66, v142
	v_mul_f32_e32 v143, s66, v143
	v_mul_f32_e32 v144, s66, v144
	v_mul_f32_e32 v145, s66, v145
	v_mul_f32_e32 v146, s66, v146
	v_mul_f32_e32 v147, s66, v147
	v_mul_f32_e32 v148, s66, v148
	v_mul_f32_e32 v149, s66, v149
	v_mul_f32_e32 v142, v142, v118
	v_mul_f32_e32 v143, v143, v119
	v_mul_f32_e32 v144, v144, v120
	v_mul_f32_e32 v145, v145, v121
	v_mul_f32_e32 v146, v146, v122
	v_mul_f32_e32 v147, v147, v123
	v_mul_f32_e32 v148, v148, v124
	v_mul_f32_e32 v149, v149, v125
	v_cvt_pk_bf16_f32 v150, v142, v143
	v_cvt_pk_bf16_f32 v151, v144, v145
	v_cvt_pk_bf16_f32 v152, v146, v147
	v_cvt_pk_bf16_f32 v153, v148, v149
	global_store_dwordx4 v169, v[150:153], s[6:7] offset:0
	s_nop 1
	s_waitcnt vmcnt(0)
; DI u32x4 pack8(const float (&v)[8]) { u32x4 r; r.x = pk2(v[0], v[1]); r.y = pk2(v[2], v[3]); r.z = pk2(v[4], v[5]); r.w = pk2(v[6], v[7]); return r; }
; __global__ void __launch_bounds__(512, 2) fwd_megakernel(Args args) {
;     ...
;                 for (int r = 0; r < 4; ++r) { const int m = m0 + r * NGW; if (m < MTOK) {
;                     const f32x4 s0 = sv[r][0], s1 = sv[r][1], s2 = sv[r][2];
;                     const float r_ssd = rsqrtf((((s0.x + s0.y) + (s0.z + s0.w)) + ((s1.x + s1.y) + (s1.z + s1.w))) * (1.f / 512.f) + EPS);
;                     const float r_att = rsqrtf(((s2.x + s2.y) + (s2.z + s2.w)) * (1.f / 256.f) + EPS);
;                     float v[8]; unpack8(yv[r][0], v);
; #pragma unroll
;                     for (int i = 0; i < 8; ++i) v[i] = v[i] * r_ssd * nwA[i];
;                     *(u32x4*)(ycat + (size_t)m * DM + colA) = pack8(v);
	v_add_u32_e32 v169, 14336, v117
	v_lshlrev_b32_e32 v142, 16, v182
	v_and_b32_e32 v143, 0xffff0000, v182
	v_lshlrev_b32_e32 v144, 16, v183
	v_and_b32_e32 v145, 0xffff0000, v183
	v_lshlrev_b32_e32 v146, 16, v184
	v_and_b32_e32 v147, 0xffff0000, v184
	v_lshlrev_b32_e32 v148, 16, v185
	v_and_b32_e32 v149, 0xffff0000, v185
	v_mul_f32_e32 v142, s67, v142
	v_mul_f32_e32 v143, s67, v143
	v_mul_f32_e32 v144, s67, v144
	v_mul_f32_e32 v145, s67, v145
	v_mul_f32_e32 v146, s67, v146
	v_mul_f32_e32 v147, s67, v147
	v_mul_f32_e32 v148, s67, v148
	v_mul_f32_e32 v149, s67, v149
	v_mul_f32_e32 v142, v142, v118
	v_mul_f32_e32 v143, v143, v119
	v_mul_f32_e32 v144, v144, v120
	v_mul_f32_e32 v145, v145, v121
	v_mul_f32_e32 v146, v146, v122
	v_mul_f32_e32 v147, v147, v123
	v_mul_f32_e32 v148, v148, v124
	v_mul_f32_e32 v149, v149, v125
	v_cvt_pk_bf16_f32 v150, v142, v143
	v_cvt_pk_bf16_f32 v151, v144, v145
	v_cvt_pk_bf16_f32 v152, v146, v147
	v_cvt_pk_bf16_f32 v153, v148, v149
	global_store_dwordx4 v169, v[150:153], s[6:7] offset:0
	s_nop 1
	v_add_u32_e32 v169, 16384, v117
	global_load_dwordx4 v[170:173], v169, s[4:5]
	v_add_u32_e32 v169, 18432, v117
	global_load_dwordx4 v[174:177], v169, s[4:5]
	v_add_u32_e32 v169, 20480, v117
	global_load_dwordx4 v[178:181], v169, s[4:5]
	v_add_u32_e32 v169, 22528, v117
	global_load_dwordx4 v[182:185], v169, s[4:5]
	s_waitcnt vmcnt(3)
	v_add_u32_e32 v169, 16384, v117
	v_lshlrev_b32_e32 v142, 16, v170
	v_and_b32_e32 v143, 0xffff0000, v170
	v_lshlrev_b32_e32 v144, 16, v171
	v_and_b32_e32 v145, 0xffff0000, v171
	v_lshlrev_b32_e32 v146, 16, v172
	v_and_b32_e32 v147, 0xffff0000, v172
	v_lshlrev_b32_e32 v148, 16, v173
	v_and_b32_e32 v149, 0xffff0000, v173
	v_mul_f32_e32 v142, s68, v142
	v_mul_f32_e32 v143, s68, v143
	v_mul_f32_e32 v144, s68, v144
	v_mul_f32_e32 v145, s68, v145
	v_mul_f32_e32 v146, s68, v146
	v_mul_f32_e32 v147, s68, v147
	v_mul_f32_e32 v148, s68, v148
	v_mul_f32_e32 v149, s68, v149
	v_mul_f32_e32 v142, v142, v118
	v_mul_f32_e32 v143, v143, v119
	v_mul_f32_e32 v144, v144, v120
	v_mul_f32_e32 v145, v145, v121
	v_mul_f32_e32 v146, v146, v122
	v_mul_f32_e32 v147, v147, v123
	v_mul_f32_e32 v148, v148, v124
	v_mul_f32_e32 v149, v149, v125
	v_cvt_pk_bf16_f32 v150, v142, v143
	v_cvt_pk_bf16_f32 v151, v144, v145
	v_cvt_pk_bf16_f32 v152, v146, v147
	v_cvt_pk_bf16_f32 v153, v148, v149
	global_store_dwordx4 v169, v[150:153], s[6:7] offset:0
	s_nop 1
	s_waitcnt vmcnt(2)
	v_add_u32_e32 v169, 18432, v117
	v_lshlrev_b32_e32 v142, 16, v174
	v_and_b32_e32 v143, 0xffff0000, v174
	v_lshlrev_b32_e32 v144, 16, v175
	v_and_b32_e32 v145, 0xffff0000, v175
	v_lshlrev_b32_e32 v146, 16, v176
	v_and_b32_e32 v147, 0xffff0000, v176
	v_lshlrev_b32_e32 v148, 16, v177
	v_and_b32_e32 v149, 0xffff0000, v177
	v_mul_f32_e32 v142, s69, v142
	v_mul_f32_e32 v143, s69, v143
	v_mul_f32_e32 v144, s69, v144
	v_mul_f32_e32 v145, s69, v145
	v_mul_f32_e32 v146, s69, v146
	v_mul_f32_e32 v147, s69, v147
	v_mul_f32_e32 v148, s69, v148
	v_mul_f32_e32 v149, s69, v149
	v_mul_f32_e32 v142, v142, v118
	v_mul_f32_e32 v143, v143, v119
	v_mul_f32_e32 v144, v144, v120
	v_mul_f32_e32 v145, v145, v121
	v_mul_f32_e32 v146, v146, v122
	v_mul_f32_e32 v147, v147, v123
	v_mul_f32_e32 v148, v148, v124
	v_mul_f32_e32 v149, v149, v125
	v_cvt_pk_bf16_f32 v150, v142, v143
	v_cvt_pk_bf16_f32 v151, v144, v145
	v_cvt_pk_bf16_f32 v152, v146, v147
	v_cvt_pk_bf16_f32 v153, v148, v149
	global_store_dwordx4 v169, v[150:153], s[6:7] offset:0
	s_nop 1
	s_waitcnt vmcnt(1)
	v_add_u32_e32 v169, 20480, v117
	v_lshlrev_b32_e32 v142, 16, v178
	v_and_b32_e32 v143, 0xffff0000, v178
	v_lshlrev_b32_e32 v144, 16, v179
	v_and_b32_e32 v145, 0xffff0000, v179
	v_lshlrev_b32_e32 v146, 16, v180
	v_and_b32_e32 v147, 0xffff0000, v180
	v_lshlrev_b32_e32 v148, 16, v181
	v_and_b32_e32 v149, 0xffff0000, v181
	v_mul_f32_e32 v142, s70, v142
	v_mul_f32_e32 v143, s70, v143
	v_mul_f32_e32 v144, s70, v144
	v_mul_f32_e32 v145, s70, v145
	v_mul_f32_e32 v146, s70, v146
	v_mul_f32_e32 v147, s70, v147
	v_mul_f32_e32 v148, s70, v148
	v_mul_f32_e32 v149, s70, v149
	v_mul_f32_e32 v142, v142, v118
	v_mul_f32_e32 v143, v143, v119
	v_mul_f32_e32 v144, v144, v120
	v_mul_f32_e32 v145, v145, v121
	v_mul_f32_e32 v146, v146, v122
	v_mul_f32_e32 v147, v147, v123
	v_mul_f32_e32 v148, v148, v124
	v_mul_f32_e32 v149, v149, v125
	v_cvt_pk_bf16_f32 v150, v142, v143
	v_cvt_pk_bf16_f32 v151, v144, v145
	v_cvt_pk_bf16_f32 v152, v146, v147
	v_cvt_pk_bf16_f32 v153, v148, v149
	global_store_dwordx4 v169, v[150:153], s[6:7] offset:0
	s_nop 1
	s_waitcnt vmcnt(0)
	v_add_u32_e32 v169, 22528, v117
	v_lshlrev_b32_e32 v142, 16, v182
	v_and_b32_e32 v143, 0xffff0000, v182
	v_lshlrev_b32_e32 v144, 16, v183
	v_and_b32_e32 v145, 0xffff0000, v183
	v_lshlrev_b32_e32 v146, 16, v184
	v_and_b32_e32 v147, 0xffff0000, v184
	v_lshlrev_b32_e32 v148, 16, v185
	v_and_b32_e32 v149, 0xffff0000, v185
	v_mul_f32_e32 v142, s71, v142
	v_mul_f32_e32 v143, s71, v143
	v_mul_f32_e32 v144, s71, v144
	v_mul_f32_e32 v145, s71, v145
	v_mul_f32_e32 v146, s71, v146
	v_mul_f32_e32 v147, s71, v147
	v_mul_f32_e32 v148, s71, v148
	v_mul_f32_e32 v149, s71, v149
	v_mul_f32_e32 v142, v142, v118
	v_mul_f32_e32 v143, v143, v119
	v_mul_f32_e32 v144, v144, v120
	v_mul_f32_e32 v145, v145, v121
	v_mul_f32_e32 v146, v146, v122
	v_mul_f32_e32 v147, v147, v123
	v_mul_f32_e32 v148, v148, v124
	v_mul_f32_e32 v149, v149, v125
	v_cvt_pk_bf16_f32 v150, v142, v143
	v_cvt_pk_bf16_f32 v151, v144, v145
	v_cvt_pk_bf16_f32 v152, v146, v147
	v_cvt_pk_bf16_f32 v153, v148, v149
	global_store_dwordx4 v169, v[150:153], s[6:7] offset:0
	s_nop 1
	v_add_u32_e32 v169, 24576, v117
	global_load_dwordx4 v[170:173], v169, s[4:5]
	v_add_u32_e32 v169, 26624, v117
	global_load_dwordx4 v[174:177], v169, s[4:5]
	v_add_u32_e32 v169, 28672, v117
	global_load_dwordx4 v[178:181], v169, s[4:5]
	v_add_u32_e32 v169, 30720, v117
	global_load_dwordx4 v[182:185], v169, s[4:5]
	s_waitcnt vmcnt(3)
; DI u32x4 pack8(const float (&v)[8]) { u32x4 r; r.x = pk2(v[0], v[1]); r.y = pk2(v[2], v[3]); r.z = pk2(v[4], v[5]); r.w = pk2(v[6], v[7]); return r; }
; __global__ void __launch_bounds__(512, 2) fwd_megakernel(Args args) {
;     ...
;                 for (int r = 0; r < 4; ++r) { const int m = m0 + r * NGW; if (m < MTOK) {
;                     const f32x4 s0 = sv[r][0], s1 = sv[r][1], s2 = sv[r][2];
;                     const float r_ssd = rsqrtf((((s0.x + s0.y) + (s0.z + s0.w)) + ((s1.x + s1.y) + (s1.z + s1.w))) * (1.f / 512.f) + EPS);
;                     const float r_att = rsqrtf(((s2.x + s2.y) + (s2.z + s2.w)) * (1.f / 256.f) + EPS);
;                     float v[8]; unpack8(yv[r][0], v);
; #pragma unroll
;                     for (int i = 0; i < 8; ++i) v[i] = v[i] * r_ssd * nwA[i];
;                     *(u32x4*)(ycat + (size_t)m * DM + colA) = pack8(v);
;                     if (lane < 32) { unpack8(yv[r][1], v);
; #pragma unroll
;                         for (int i = 0; i < 8; ++i) v[i] = v[i] * r_att * nwB[i];
;                         *(u32x4*)(ycat + (size_t)m * DM + colB) = pack8(v); } } }
	v_add_u32_e32 v169, 24576, v117
	v_lshlrev_b32_e32 v142, 16, v170
	v_and_b32_e32 v143, 0xffff0000, v170
	v_lshlrev_b32_e32 v144, 16, v171
	v_and_b32_e32 v145, 0xffff0000, v171
	v_lshlrev_b32_e32 v146, 16, v172
	v_and_b32_e32 v147, 0xffff0000, v172
	v_lshlrev_b32_e32 v148, 16, v173
	v_and_b32_e32 v149, 0xffff0000, v173
	v_mul_f32_e32 v142, s72, v142
	v_mul_f32_e32 v143, s72, v143
	v_mul_f32_e32 v144, s72, v144
	v_mul_f32_e32 v145, s72, v145
	v_mul_f32_e32 v146, s72, v146
	v_mul_f32_e32 v147, s72, v147
	v_mul_f32_e32 v148, s72, v148
	v_mul_f32_e32 v149, s72, v149
	v_mul_f32_e32 v142, v142, v118
	v_mul_f32_e32 v143, v143, v119
	v_mul_f32_e32 v144, v144, v120
	v_mul_f32_e32 v145, v145, v121
	v_mul_f32_e32 v146, v146, v122
	v_mul_f32_e32 v147, v147, v123
	v_mul_f32_e32 v148, v148, v124
	v_mul_f32_e32 v149, v149, v125
	v_cvt_pk_bf16_f32 v150, v142, v143
	v_cvt_pk_bf16_f32 v151, v144, v145
	v_cvt_pk_bf16_f32 v152, v146, v147
	v_cvt_pk_bf16_f32 v153, v148, v149
	global_store_dwordx4 v169, v[150:153], s[6:7] offset:0
	s_nop 1
	s_waitcnt vmcnt(2)
	v_add_u32_e32 v169, 26624, v117
	v_lshlrev_b32_e32 v142, 16, v174
	v_and_b32_e32 v143, 0xffff0000, v174
	v_lshlrev_b32_e32 v144, 16, v175
	v_and_b32_e32 v145, 0xffff0000, v175
	v_lshlrev_b32_e32 v146, 16, v176
	v_and_b32_e32 v147, 0xffff0000, v176
	v_lshlrev_b32_e32 v148, 16, v177
	v_and_b32_e32 v149, 0xffff0000, v177
	v_mul_f32_e32 v142, s73, v142
	v_mul_f32_e32 v143, s73, v143
	v_mul_f32_e32 v144, s73, v144
	v_mul_f32_e32 v145, s73, v145
	v_mul_f32_e32 v146, s73, v146
	v_mul_f32_e32 v147, s73, v147
	v_mul_f32_e32 v148, s73, v148
	v_mul_f32_e32 v149, s73, v149
	v_mul_f32_e32 v142, v142, v118
	v_mul_f32_e32 v143, v143, v119
	v_mul_f32_e32 v144, v144, v120
	v_mul_f32_e32 v145, v145, v121
	v_mul_f32_e32 v146, v146, v122
	v_mul_f32_e32 v147, v147, v123
	v_mul_f32_e32 v148, v148, v124
	v_mul_f32_e32 v149, v149, v125
	v_cvt_pk_bf16_f32 v150, v142, v143
	v_cvt_pk_bf16_f32 v151, v144, v145
	v_cvt_pk_bf16_f32 v152, v146, v147
	v_cvt_pk_bf16_f32 v153, v148, v149
	global_store_dwordx4 v169, v[150:153], s[6:7] offset:0
	s_nop 1
	s_waitcnt vmcnt(1)
	v_add_u32_e32 v169, 28672, v117
	v_lshlrev_b32_e32 v142, 16, v178
	v_and_b32_e32 v143, 0xffff0000, v178
	v_lshlrev_b32_e32 v144, 16, v179
	v_and_b32_e32 v145, 0xffff0000, v179
	v_lshlrev_b32_e32 v146, 16, v180
	v_and_b32_e32 v147, 0xffff0000, v180
	v_lshlrev_b32_e32 v148, 16, v181
	v_and_b32_e32 v149, 0xffff0000, v181
	v_mul_f32_e32 v142, s74, v142
	v_mul_f32_e32 v143, s74, v143
	v_mul_f32_e32 v144, s74, v144
	v_mul_f32_e32 v145, s74, v145
	v_mul_f32_e32 v146, s74, v146
	v_mul_f32_e32 v147, s74, v147
	v_mul_f32_e32 v148, s74, v148
	v_mul_f32_e32 v149, s74, v149
	v_mul_f32_e32 v142, v142, v118
	v_mul_f32_e32 v143, v143, v119
	v_mul_f32_e32 v144, v144, v120
	v_mul_f32_e32 v145, v145, v121
	v_mul_f32_e32 v146, v146, v122
	v_mul_f32_e32 v147, v147, v123
	v_mul_f32_e32 v148, v148, v124
	v_mul_f32_e32 v149, v149, v125
	v_cvt_pk_bf16_f32 v150, v142, v143
	v_cvt_pk_bf16_f32 v151, v144, v145
	v_cvt_pk_bf16_f32 v152, v146, v147
	v_cvt_pk_bf16_f32 v153, v148, v149
	global_store_dwordx4 v169, v[150:153], s[6:7] offset:0
	s_nop 1
	s_waitcnt vmcnt(0)
	v_add_u32_e32 v169, 30720, v117
	v_lshlrev_b32_e32 v142, 16, v182
	v_and_b32_e32 v143, 0xffff0000, v182
	v_lshlrev_b32_e32 v144, 16, v183
	v_and_b32_e32 v145, 0xffff0000, v183
	v_lshlrev_b32_e32 v146, 16, v184
	v_and_b32_e32 v147, 0xffff0000, v184
	v_lshlrev_b32_e32 v148, 16, v185
	v_and_b32_e32 v149, 0xffff0000, v185
	v_mul_f32_e32 v142, s75, v142
	v_mul_f32_e32 v143, s75, v143
	v_mul_f32_e32 v144, s75, v144
	v_mul_f32_e32 v145, s75, v145
	v_mul_f32_e32 v146, s75, v146
	v_mul_f32_e32 v147, s75, v147
	v_mul_f32_e32 v148, s75, v148
	v_mul_f32_e32 v149, s75, v149
	v_mul_f32_e32 v142, v142, v118
	v_mul_f32_e32 v143, v143, v119
	v_mul_f32_e32 v144, v144, v120
	v_mul_f32_e32 v145, v145, v121
	v_mul_f32_e32 v146, v146, v122
	v_mul_f32_e32 v147, v147, v123
	v_mul_f32_e32 v148, v148, v124
	v_mul_f32_e32 v149, v149, v125
	v_cvt_pk_bf16_f32 v150, v142, v143
	v_cvt_pk_bf16_f32 v151, v144, v145
	v_cvt_pk_bf16_f32 v152, v146, v147
	v_cvt_pk_bf16_f32 v153, v148, v149
	global_store_dwordx4 v169, v[150:153], s[6:7] offset:0
	s_nop 1
	v_lshrrev_b32_e32 v162, 5, v116
	v_and_b32_e32 v164, 31, v116
	v_lshlrev_b32_e32 v164, 4, v164
	v_lshl_add_u32 v164, v162, 11, v164
	v_add_u32_e32 v164, 0x400, v164
	v_add_u32_e32 v169, 0, v164
	global_load_dwordx4 v[170:173], v169, s[4:5]
	v_add_u32_e32 v169, 4096, v164
	global_load_dwordx4 v[174:177], v169, s[4:5]
	v_add_u32_e32 v169, 8192, v164
	global_load_dwordx4 v[178:181], v169, s[4:5]
	v_add_u32_e32 v169, 12288, v164
	global_load_dwordx4 v[182:185], v169, s[4:5]
	v_add_u32_e32 v163, 0, v162
	v_lshlrev_b32_e32 v163, 2, v163
	ds_bpermute_b32 v168, v163, v160
	s_waitcnt vmcnt(3) lgkmcnt(0)
	v_add_u32_e32 v169, 0, v164
	v_lshlrev_b32_e32 v142, 16, v170
	v_and_b32_e32 v143, 0xffff0000, v170
	v_lshlrev_b32_e32 v144, 16, v171
	v_and_b32_e32 v145, 0xffff0000, v171
	v_lshlrev_b32_e32 v146, 16, v172
	v_and_b32_e32 v147, 0xffff0000, v172
	v_lshlrev_b32_e32 v148, 16, v173
	v_and_b32_e32 v149, 0xffff0000, v173
	v_mul_f32_e32 v142, v142, v168
	v_mul_f32_e32 v143, v143, v168
	v_mul_f32_e32 v144, v144, v168
	v_mul_f32_e32 v145, v145, v168
	v_mul_f32_e32 v146, v146, v168
	v_mul_f32_e32 v147, v147, v168
	v_mul_f32_e32 v148, v148, v168
	v_mul_f32_e32 v149, v149, v168
	v_mul_f32_e32 v142, v142, v126
	v_mul_f32_e32 v143, v143, v127
	v_mul_f32_e32 v144, v144, v128
	v_mul_f32_e32 v145, v145, v129
	v_mul_f32_e32 v146, v146, v130
	v_mul_f32_e32 v147, v147, v131
	v_mul_f32_e32 v148, v148, v132
	v_mul_f32_e32 v149, v149, v133
	v_cvt_pk_bf16_f32 v150, v142, v143
	v_cvt_pk_bf16_f32 v151, v144, v145
	v_cvt_pk_bf16_f32 v152, v146, v147
	v_cvt_pk_bf16_f32 v153, v148, v149
	global_store_dwordx4 v169, v[150:153], s[6:7] offset:0
	s_nop 1
	v_add_u32_e32 v163, 2, v162
	v_lshlrev_b32_e32 v163, 2, v163
	ds_bpermute_b32 v168, v163, v160
	s_waitcnt vmcnt(2) lgkmcnt(0)
; DI u32x4 pack8(const float (&v)[8]) { u32x4 r; r.x = pk2(v[0], v[1]); r.y = pk2(v[2], v[3]); r.z = pk2(v[4], v[5]); r.w = pk2(v[6], v[7]); return r; }
; __global__ void __launch_bounds__(512, 2) fwd_megakernel(Args args) {
;     ...
;                     if (lane < 32) { unpack8(yv[r][1], v);
; #pragma unroll
;                         for (int i = 0; i < 8; ++i) v[i] = v[i] * r_att * nwB[i];
;                         *(u32x4*)(ycat + (size_t)m * DM + colB) = pack8(v); } } }
	v_add_u32_e32 v169, 4096, v164
	v_lshlrev_b32_e32 v142, 16, v174
	v_and_b32_e32 v143, 0xffff0000, v174
	v_lshlrev_b32_e32 v144, 16, v175
	v_and_b32_e32 v145, 0xffff0000, v175
	v_lshlrev_b32_e32 v146, 16, v176
	v_and_b32_e32 v147, 0xffff0000, v176
	v_lshlrev_b32_e32 v148, 16, v177
	v_and_b32_e32 v149, 0xffff0000, v177
	v_mul_f32_e32 v142, v142, v168
	v_mul_f32_e32 v143, v143, v168
	v_mul_f32_e32 v144, v144, v168
	v_mul_f32_e32 v145, v145, v168
	v_mul_f32_e32 v146, v146, v168
	v_mul_f32_e32 v147, v147, v168
	v_mul_f32_e32 v148, v148, v168
	v_mul_f32_e32 v149, v149, v168
	v_mul_f32_e32 v142, v142, v126
	v_mul_f32_e32 v143, v143, v127
	v_mul_f32_e32 v144, v144, v128
	v_mul_f32_e32 v145, v145, v129
	v_mul_f32_e32 v146, v146, v130
	v_mul_f32_e32 v147, v147, v131
	v_mul_f32_e32 v148, v148, v132
	v_mul_f32_e32 v149, v149, v133
	v_cvt_pk_bf16_f32 v150, v142, v143
	v_cvt_pk_bf16_f32 v151, v144, v145
	v_cvt_pk_bf16_f32 v152, v146, v147
	v_cvt_pk_bf16_f32 v153, v148, v149
	global_store_dwordx4 v169, v[150:153], s[6:7] offset:0
	s_nop 1
	v_add_u32_e32 v163, 4, v162
	v_lshlrev_b32_e32 v163, 2, v163
	ds_bpermute_b32 v168, v163, v160
	s_waitcnt vmcnt(1) lgkmcnt(0)
	v_add_u32_e32 v169, 8192, v164
	v_lshlrev_b32_e32 v142, 16, v178
	v_and_b32_e32 v143, 0xffff0000, v178
	v_lshlrev_b32_e32 v144, 16, v179
	v_and_b32_e32 v145, 0xffff0000, v179
	v_lshlrev_b32_e32 v146, 16, v180
	v_and_b32_e32 v147, 0xffff0000, v180
	v_lshlrev_b32_e32 v148, 16, v181
	v_and_b32_e32 v149, 0xffff0000, v181
	v_mul_f32_e32 v142, v142, v168
	v_mul_f32_e32 v143, v143, v168
	v_mul_f32_e32 v144, v144, v168
	v_mul_f32_e32 v145, v145, v168
	v_mul_f32_e32 v146, v146, v168
	v_mul_f32_e32 v147, v147, v168
	v_mul_f32_e32 v148, v148, v168
	v_mul_f32_e32 v149, v149, v168
	v_mul_f32_e32 v142, v142, v126
	v_mul_f32_e32 v143, v143, v127
	v_mul_f32_e32 v144, v144, v128
	v_mul_f32_e32 v145, v145, v129
	v_mul_f32_e32 v146, v146, v130
	v_mul_f32_e32 v147, v147, v131
	v_mul_f32_e32 v148, v148, v132
	v_mul_f32_e32 v149, v149, v133
	v_cvt_pk_bf16_f32 v150, v142, v143
	v_cvt_pk_bf16_f32 v151, v144, v145
	v_cvt_pk_bf16_f32 v152, v146, v147
	v_cvt_pk_bf16_f32 v153, v148, v149
	global_store_dwordx4 v169, v[150:153], s[6:7] offset:0
	s_nop 1
	v_add_u32_e32 v163, 6, v162
	v_lshlrev_b32_e32 v163, 2, v163
	ds_bpermute_b32 v168, v163, v160
	s_waitcnt vmcnt(0) lgkmcnt(0)
	v_add_u32_e32 v169, 12288, v164
	v_lshlrev_b32_e32 v142, 16, v182
	v_and_b32_e32 v143, 0xffff0000, v182
	v_lshlrev_b32_e32 v144, 16, v183
	v_and_b32_e32 v145, 0xffff0000, v183
	v_lshlrev_b32_e32 v146, 16, v184
	v_and_b32_e32 v147, 0xffff0000, v184
	v_lshlrev_b32_e32 v148, 16, v185
	v_and_b32_e32 v149, 0xffff0000, v185
	v_mul_f32_e32 v142, v142, v168
	v_mul_f32_e32 v143, v143, v168
	v_mul_f32_e32 v144, v144, v168
	v_mul_f32_e32 v145, v145, v168
	v_mul_f32_e32 v146, v146, v168
	v_mul_f32_e32 v147, v147, v168
	v_mul_f32_e32 v148, v148, v168
	v_mul_f32_e32 v149, v149, v168
	v_mul_f32_e32 v142, v142, v126
	v_mul_f32_e32 v143, v143, v127
	v_mul_f32_e32 v144, v144, v128
	v_mul_f32_e32 v145, v145, v129
	v_mul_f32_e32 v146, v146, v130
	v_mul_f32_e32 v147, v147, v131
	v_mul_f32_e32 v148, v148, v132
	v_mul_f32_e32 v149, v149, v133
	v_cvt_pk_bf16_f32 v150, v142, v143
	v_cvt_pk_bf16_f32 v151, v144, v145
	v_cvt_pk_bf16_f32 v152, v146, v147
	v_cvt_pk_bf16_f32 v153, v148, v149
	global_store_dwordx4 v169, v[150:153], s[6:7] offset:0
	s_nop 1
	v_add_u32_e32 v169, 16384, v164
	global_load_dwordx4 v[170:173], v169, s[4:5]
	v_add_u32_e32 v169, 20480, v164
	global_load_dwordx4 v[174:177], v169, s[4:5]
	v_add_u32_e32 v169, 24576, v164
	global_load_dwordx4 v[178:181], v169, s[4:5]
	v_add_u32_e32 v169, 28672, v164
	global_load_dwordx4 v[182:185], v169, s[4:5]
	v_add_u32_e32 v163, 8, v162
	v_lshlrev_b32_e32 v163, 2, v163
	ds_bpermute_b32 v168, v163, v160
	s_waitcnt vmcnt(3) lgkmcnt(0)
	v_add_u32_e32 v169, 16384, v164
	v_lshlrev_b32_e32 v142, 16, v170
	v_and_b32_e32 v143, 0xffff0000, v170
	v_lshlrev_b32_e32 v144, 16, v171
	v_and_b32_e32 v145, 0xffff0000, v171
	v_lshlrev_b32_e32 v146, 16, v172
	v_and_b32_e32 v147, 0xffff0000, v172
	v_lshlrev_b32_e32 v148, 16, v173
	v_and_b32_e32 v149, 0xffff0000, v173
	v_mul_f32_e32 v142, v142, v168
	v_mul_f32_e32 v143, v143, v168
	v_mul_f32_e32 v144, v144, v168
	v_mul_f32_e32 v145, v145, v168
	v_mul_f32_e32 v146, v146, v168
	v_mul_f32_e32 v147, v147, v168
	v_mul_f32_e32 v148, v148, v168
	v_mul_f32_e32 v149, v149, v168
	v_mul_f32_e32 v142, v142, v126
	v_mul_f32_e32 v143, v143, v127
	v_mul_f32_e32 v144, v144, v128
	v_mul_f32_e32 v145, v145, v129
	v_mul_f32_e32 v146, v146, v130
	v_mul_f32_e32 v147, v147, v131
	v_mul_f32_e32 v148, v148, v132
	v_mul_f32_e32 v149, v149, v133
	v_cvt_pk_bf16_f32 v150, v142, v143
	v_cvt_pk_bf16_f32 v151, v144, v145
	v_cvt_pk_bf16_f32 v152, v146, v147
	v_cvt_pk_bf16_f32 v153, v148, v149
	global_store_dwordx4 v169, v[150:153], s[6:7] offset:0
	s_nop 1
	v_add_u32_e32 v163, 10, v162
	v_lshlrev_b32_e32 v163, 2, v163
	ds_bpermute_b32 v168, v163, v160
	s_waitcnt vmcnt(2) lgkmcnt(0)
; DI u32x4 pack8(const float (&v)[8]) { u32x4 r; r.x = pk2(v[0], v[1]); r.y = pk2(v[2], v[3]); r.z = pk2(v[4], v[5]); r.w = pk2(v[6], v[7]); return r; }
; __global__ void __launch_bounds__(512, 2) fwd_megakernel(Args args) {
;     ...
;                     if (lane < 32) { unpack8(yv[r][1], v);
; #pragma unroll
;                         for (int i = 0; i < 8; ++i) v[i] = v[i] * r_att * nwB[i];
;                         *(u32x4*)(ycat + (size_t)m * DM + colB) = pack8(v); } } }
	v_add_u32_e32 v169, 20480, v164
	v_lshlrev_b32_e32 v142, 16, v174
	v_and_b32_e32 v143, 0xffff0000, v174
	v_lshlrev_b32_e32 v144, 16, v175
	v_and_b32_e32 v145, 0xffff0000, v175
	v_lshlrev_b32_e32 v146, 16, v176
	v_and_b32_e32 v147, 0xffff0000, v176
	v_lshlrev_b32_e32 v148, 16, v177
	v_and_b32_e32 v149, 0xffff0000, v177
	v_mul_f32_e32 v142, v142, v168
	v_mul_f32_e32 v143, v143, v168
	v_mul_f32_e32 v144, v144, v168
	v_mul_f32_e32 v145, v145, v168
	v_mul_f32_e32 v146, v146, v168
	v_mul_f32_e32 v147, v147, v168
	v_mul_f32_e32 v148, v148, v168
	v_mul_f32_e32 v149, v149, v168
	v_mul_f32_e32 v142, v142, v126
	v_mul_f32_e32 v143, v143, v127
	v_mul_f32_e32 v144, v144, v128
	v_mul_f32_e32 v145, v145, v129
	v_mul_f32_e32 v146, v146, v130
	v_mul_f32_e32 v147, v147, v131
	v_mul_f32_e32 v148, v148, v132
	v_mul_f32_e32 v149, v149, v133
	v_cvt_pk_bf16_f32 v150, v142, v143
	v_cvt_pk_bf16_f32 v151, v144, v145
	v_cvt_pk_bf16_f32 v152, v146, v147
	v_cvt_pk_bf16_f32 v153, v148, v149
	global_store_dwordx4 v169, v[150:153], s[6:7] offset:0
	s_nop 1
	v_add_u32_e32 v163, 12, v162
	v_lshlrev_b32_e32 v163, 2, v163
	ds_bpermute_b32 v168, v163, v160
	s_waitcnt vmcnt(1) lgkmcnt(0)
	v_add_u32_e32 v169, 24576, v164
	v_lshlrev_b32_e32 v142, 16, v178
	v_and_b32_e32 v143, 0xffff0000, v178
	v_lshlrev_b32_e32 v144, 16, v179
	v_and_b32_e32 v145, 0xffff0000, v179
	v_lshlrev_b32_e32 v146, 16, v180
	v_and_b32_e32 v147, 0xffff0000, v180
	v_lshlrev_b32_e32 v148, 16, v181
	v_and_b32_e32 v149, 0xffff0000, v181
	v_mul_f32_e32 v142, v142, v168
	v_mul_f32_e32 v143, v143, v168
	v_mul_f32_e32 v144, v144, v168
	v_mul_f32_e32 v145, v145, v168
	v_mul_f32_e32 v146, v146, v168
	v_mul_f32_e32 v147, v147, v168
	v_mul_f32_e32 v148, v148, v168
	v_mul_f32_e32 v149, v149, v168
	v_mul_f32_e32 v142, v142, v126
	v_mul_f32_e32 v143, v143, v127
	v_mul_f32_e32 v144, v144, v128
	v_mul_f32_e32 v145, v145, v129
	v_mul_f32_e32 v146, v146, v130
	v_mul_f32_e32 v147, v147, v131
	v_mul_f32_e32 v148, v148, v132
	v_mul_f32_e32 v149, v149, v133
	v_cvt_pk_bf16_f32 v150, v142, v143
	v_cvt_pk_bf16_f32 v151, v144, v145
	v_cvt_pk_bf16_f32 v152, v146, v147
	v_cvt_pk_bf16_f32 v153, v148, v149
	global_store_dwordx4 v169, v[150:153], s[6:7] offset:0
	s_nop 1
	v_add_u32_e32 v163, 14, v162
	v_lshlrev_b32_e32 v163, 2, v163
	ds_bpermute_b32 v168, v163, v160
	s_waitcnt vmcnt(0) lgkmcnt(0)
	v_add_u32_e32 v169, 28672, v164
	v_lshlrev_b32_e32 v142, 16, v182
	v_and_b32_e32 v143, 0xffff0000, v182
	v_lshlrev_b32_e32 v144, 16, v183
	v_and_b32_e32 v145, 0xffff0000, v183
	v_lshlrev_b32_e32 v146, 16, v184
	v_and_b32_e32 v147, 0xffff0000, v184
	v_lshlrev_b32_e32 v148, 16, v185
	v_and_b32_e32 v149, 0xffff0000, v185
	v_mul_f32_e32 v142, v142, v168
	v_mul_f32_e32 v143, v143, v168
	v_mul_f32_e32 v144, v144, v168
	v_mul_f32_e32 v145, v145, v168
	v_mul_f32_e32 v146, v146, v168
	v_mul_f32_e32 v147, v147, v168
	v_mul_f32_e32 v148, v148, v168
	v_mul_f32_e32 v149, v149, v168
	v_mul_f32_e32 v142, v142, v126
	v_mul_f32_e32 v143, v143, v127
	v_mul_f32_e32 v144, v144, v128
	v_mul_f32_e32 v145, v145, v129
	v_mul_f32_e32 v146, v146, v130
	v_mul_f32_e32 v147, v147, v131
	v_mul_f32_e32 v148, v148, v132
	v_mul_f32_e32 v149, v149, v133
	v_cvt_pk_bf16_f32 v150, v142, v143
	v_cvt_pk_bf16_f32 v151, v144, v145
	v_cvt_pk_bf16_f32 v152, v146, v147
	v_cvt_pk_bf16_f32 v153, v148, v149
	global_store_dwordx4 v169, v[150:153], s[6:7] offset:0
	s_nop 1
	v_readlane_b32 s76, v251, 57
	v_readlane_b32 s77, v251, 58
	v_readlane_b32 s52, v251, 61
	v_readlane_b32 s78, v253, 42
	v_readlane_b32 s53, v251, 62
	v_readlane_b32 s72, v251, 59
	v_readlane_b32 s79, v253, 43
	v_readlane_b32 s51, v251, 63
	v_readlane_b32 s54, v251, 0
	v_readlane_b32 s73, v251, 60
	s_mul_i32 s55, s82, 24
	v_readlane_b32 s74, v253, 27
	v_readlane_b32 s75, v253, 28
	v_readlane_b32 s79, v253, 29
	v_readlane_b32 s83, v253, 30
	v_readlane_b32 s53, v253, 26
	s_nop 4
	s_branch .LBB0_1129
